# grid barrier: every waiter (non-leaders and non-last XCD leaders) polls the top-level arrival counter against nx*(gen+1); generation-word hops removed from the release path
# baseline (speedup 1.0000x reference)
.LBB0_170:
	s_or_b64 exec, exec, s[6:7]
	v_cvt_f32_u32_e32 v4, v2
	s_waitcnt vmcnt(0)
	v_readfirstlane_b32 s0, v3
	v_sub_u32_e32 v3, 0, v2
	v_rcp_iflag_f32_e32 v4, v4
	v_add_u32_e32 v5, s0, v1
	v_mul_f32_e32 v4, 0x4f7ffffe, v4
	v_cvt_u32_f32_e32 v4, v4
	v_mul_lo_u32 v1, v3, v4
	v_mul_hi_u32 v1, v4, v1
	v_add_u32_e32 v1, v4, v1
	v_mul_hi_u32 v1, v5, v1
	v_mul_lo_u32 v3, v1, v2
	v_sub_u32_e32 v3, v5, v3
	v_add_u32_e32 v4, 1, v1
	v_cmp_ge_u32_e32 vcc, v3, v2
	s_nop 1
	v_cndmask_b32_e32 v1, v1, v4, vcc
	v_sub_u32_e32 v4, v3, v2
	v_cndmask_b32_e32 v3, v3, v4, vcc
	v_add_u32_e32 v4, 1, v1
	v_cmp_ge_u32_e32 vcc, v3, v2
	v_add_u32_e32 v3, 1, v5
	s_nop 0
	v_cndmask_b32_e32 v1, v1, v4, vcc
	v_mul_lo_u32 v4, v2, v1
	v_add_u32_e32 v2, v4, v2
	v_cmp_ne_u32_e32 vcc, v3, v2
	s_and_saveexec_b64 s[0:1], vcc
	s_xor_b64 s[6:7], exec, s[0:1]
	s_cbranch_execz .LBB0_184
	v_mad_u32_u24 v16, v0, v1, v0
	v_readlane_b32 s0, v254, 33
	v_readlane_b32 s1, v254, 34
	s_waitcnt lgkmcnt(0)
	s_nop 3
	global_load_dword v0, v131, s[0:1] sc1
	s_waitcnt vmcnt(0)
	v_cmp_lt_u32_e32 vcc, v0, v16
	s_and_saveexec_b64 s[8:9], vcc
	s_cbranch_execz .LBB0_183
	s_mov_b32 s0, 1
	s_mov_b64 s[10:11], 0
	s_branch .LBB0_174

.LBB0_178:
	v_readlane_b32 s12, v254, 33
	v_readlane_b32 s13, v254, 34
	s_add_i32 s0, s0, 1
	s_mov_b64 s[28:29], -1
	s_nop 2
	global_load_dword v0, v131, s[12:13] sc1
	s_waitcnt vmcnt(0)
	v_cmp_ge_u32_e32 vcc, v0, v16
	s_orn2_b64 s[18:19], vcc, exec
	s_branch .LBB0_173

.LBB0_187:
	s_or_b64 exec, exec, s[8:9]
	s_waitcnt vmcnt(0)
	v_readfirstlane_b32 s0, v2
	v_cvt_f32_u32_e32 v2, v0
	v_sub_u32_e32 v3, 0, v0
	v_add_u32_e32 v1, s0, v1
	v_readlane_b32 s0, v254, 35
	v_rcp_iflag_f32_e32 v2, v2
	v_readlane_b32 s1, v254, 36
	s_mov_b64 s[8:9], -1
	v_mul_f32_e32 v2, 0x4f7ffffe, v2
	v_cvt_u32_f32_e32 v2, v2
	v_mul_lo_u32 v3, v3, v2
	v_mul_hi_u32 v3, v2, v3
	v_add_u32_e32 v2, v2, v3
	v_mul_hi_u32 v2, v1, v2
	v_mul_lo_u32 v3, v2, v0
	v_sub_u32_e32 v3, v1, v3
	v_cmp_ge_u32_e32 vcc, v3, v0
	v_add_u32_e32 v4, 1, v2
	v_add_u32_e32 v1, 1, v1
	v_cndmask_b32_e32 v2, v2, v4, vcc
	v_sub_u32_e32 v4, v3, v0
	v_cndmask_b32_e32 v3, v3, v4, vcc
	v_cmp_ge_u32_e32 vcc, v3, v0
	v_add_u32_e32 v3, 1, v2
	s_nop 0
	v_cndmask_b32_e32 v2, v2, v3, vcc
	v_mul_lo_u32 v3, v0, v2
	v_add_u32_e32 v0, v3, v0
	v_mov_b32_e32 v16, v0
	v_cmp_ne_u32_e32 vcc, v1, v0
	v_mov_b64_e32 v[0:1], s[0:1]
	s_and_saveexec_b64 s[6:7], vcc
	s_cbranch_execz .LBB0_199
	v_readlane_b32 s0, v254, 33
	v_readlane_b32 s1, v254, 34
	s_mov_b64 s[10:11], 0
	s_nop 3
	global_load_dword v0, v131, s[0:1] sc1
	s_waitcnt vmcnt(0)
	v_cmp_lt_u32_e32 vcc, v0, v16
	s_and_saveexec_b64 s[8:9], vcc
	s_cbranch_execz .LBB0_198
	s_mov_b32 s0, 1
	s_branch .LBB0_191
